# plain-copy units: half moved from attention phase into gate/up GEMM K-loop (2 buffer_load/store slots per iteration, counted vmcnt adjusted)
# baseline (speedup 1.0000x reference)
.LBB0_1208:
	s_add_i32 s95, s95, 1
	s_mul_i32 s8, s95, s40
	s_mov_b32 s82, s40
	s_cmpk_gt_i32 s8, 0x37ff
	s_cbranch_scc1 .LBB0_1379
.LBB0_1209:
	v_readlane_b32 s10, v240, 0
	s_add_i32 s12, s8, s10
	s_lshl_b32 s8, s95, 8
	s_add_i32 s8, s8, s15
	s_ashr_i32 s9, s8, 7
	v_readlane_b32 s11, v240, 1
	s_mul_hi_i32 s10, s9, 0x55555556
	s_lshr_b32 s11, s10, 31
	s_add_i32 s10, s10, s11
	s_mul_i32 s11, s14, 3
	s_add_i32 s11, s10, s11
	s_mul_i32 s10, s10, 3
	s_mul_i32 s11, s11, 3
	s_sub_i32 s10, s9, s10
	s_add_i32 s11, s11, s10
	s_mul_hi_i32 s10, s8, 0x30c30c31
	s_lshr_b32 s16, s10, 31
	s_ashr_i32 s10, s10, 4
	s_add_i32 s10, s10, s16
	s_lshl_b32 s16, s10, 3
	s_or_b32 s16, s16, s14
	s_mulk_i32 s10, 0x54
	s_mulk_i32 s16, 0x54
	s_sub_i32 s10, s8, s10
	s_add_i32 s13, s12, 0x2a00
	s_add_i32 s96, s12, 0xffffe200
	s_add_i32 s16, s16, s10
	s_cmp_lt_u32 s9, 12
	s_cselect_b32 s10, s19, s2
	s_add_i32 s10, s10, s9
	s_cmp_lt_i32 s9, 9
	s_cselect_b32 s9, s11, s10
	s_lshl_b32 s9, s9, 7
	s_add_i32 s17, s9, s35
	s_cmpk_lt_i32 s8, 0x540
	s_cselect_b32 s10, s16, -1
	s_and_b64 s[8:9], s[58:59], exec
	s_cselect_b32 s16, s12, s10
	s_cmpk_gt_i32 s12, 0x29ff
	s_cselect_b64 s[8:9], -1, 0
	s_and_b64 s[10:11], s[8:9], exec
	s_cselect_b32 s97, -1, s16
	s_or_b64 s[8:9], s[8:9], s[58:59]
	s_cmpk_lt_u32 s96, 0x1800
	s_cselect_b64 s[10:11], -1, 0
	s_and_b64 s[74:75], s[8:9], s[10:11]
	s_and_b64 s[8:9], s[58:59], exec
	s_cselect_b32 s8, s13, s17
	s_cmpk_lt_i32 s12, 0x3800
	s_mov_b32 s40, s82
	s_cselect_b32 s52, s8, -1
	s_mov_b64 s[76:77], -1
	s_mov_b32 s10, s57
	s_branch .LBB0_1212

.LBB0_1649:
	s_or_b64 exec, exec, s[6:7]
	s_add_u32 s8, s30, 0xfc00000
	s_addc_u32 s9, s31, 0
	v_mov_b32_e32 v10, v164
	s_waitcnt lgkmcnt(0)
	s_barrier
	s_cmpk_gt_i32 s69, 0x5d7
	v_readfirstlane_b32 s7, v10
	s_cbranch_scc1 .LBB0_1665
	v_writelane_b32 v247, s78, 0
	v_writelane_b32 v247, s79, 1
	v_writelane_b32 v247, s4, 2
	s_lshr_b32 s32, s69, 7
	s_lshl_b32 s32, s32, 3
	s_load_dwordx2 s[96:97], s[0:1], s32 offset:0x20
	s_load_dwordx2 s[76:77], s[0:1], 0xa0
	s_and_b32 s100, s69, 0x7f
	s_mul_i32 s100, s100, 0x300000
	s_lshr_b32 s101, s7, 6
	s_mul_i32 s101, s101, 0x24000
	s_add_u32 s100, s100, s101
	s_mov_b32 s101, 0x1ee80000
	s_cmp_lt_u32 s69, 0x80
	s_cselect_b32 s101, 0x6e80000, s101
	v_and_b32_e32 v246, 63, v164
	v_lshlrev_b32_e32 v246, 4, v246
	s_waitcnt lgkmcnt(0)
	s_add_u32 s96, s96, s100
	s_addc_u32 s97, s97, 0
	s_add_u32 s96, s96, 0x3000
	s_addc_u32 s97, s97, 0
	s_and_b32 s97, s97, 0xffff
	s_mov_b32 s98, 0x26000
	s_mov_b32 s99, 0x20000
	s_add_u32 s76, s76, s101
	s_addc_u32 s77, s77, 0
	s_add_u32 s76, s76, s100
	s_addc_u32 s77, s77, 0
	s_and_b32 s77, s77, 0xffff
	s_mov_b32 s78, 0x26000
	s_mov_b32 s79, 0x20000
	s_mov_b32 s100, 0x800
	s_mov_b32 s101, 0
	s_mov_b32 s32, 1
	s_mov_b32 s4, 36
	buffer_load_dwordx4 v[228:231], v246, s[96:99], 0 offen offset:0 nt
	buffer_load_dwordx4 v[232:235], v246, s[96:99], 0 offen offset:1024 nt
	v_lshlrev_b32_e32 v0, 4, v10
	v_add_u32_e32 v1, 0x2000, v0
	v_ashrrev_i32_e32 v2, 31, v1
	v_lshrrev_b32_e32 v2, 22, v2
	v_add_u32_e32 v2, v1, v2
	v_ashrrev_i32_e32 v8, 10, v2
	v_mul_i32_i24_e32 v2, 0x400, v8
	v_sub_u32_e32 v1, v1, v2
	v_lshrrev_b32_e32 v2, 4, v1
	v_bitop3_b32 v1, v2, v1, 32 bitop3:0x6c
	v_ashrrev_i32_e32 v2, 31, v1
	v_lshrrev_b32_e32 v2, 26, v2
	v_add_u32_e32 v2, v1, v2
	v_lshlrev_b32_e32 v3, 3, v8
	v_ashrrev_i32_e32 v9, 6, v2
	v_and_b32_e32 v3, -16, v3
	v_add_u32_e32 v3, v9, v3
	v_and_b32_e32 v4, 3, v9
	s_mov_b32 s6, 0x1fffe0
	v_lshrrev_b32_e32 v5, 2, v3
	v_lshlrev_b32_e32 v6, 1, v3
	v_and_b32_e32 v2, 0xc0, v2
	v_and_or_b32 v4, v3, s6, v4
	v_and_b32_e32 v5, 4, v5
	v_and_b32_e32 v6, 24, v6
	v_sub_u32_e32 v1, v1, v2
	v_mov_b32_e32 v2, 1
	v_or3_b32 v4, v4, v5, v6
	v_lshlrev_b32_e32 v5, 5, v8
	v_ashrrev_i16_sdwa v1, v2, sext(v1) dst_sel:DWORD dst_unused:UNUSED_PAD src0_sel:DWORD src1_sel:BYTE_0
	v_and_b32_e32 v5, 32, v5
	v_bfe_i32 v11, v1, 0, 16
	v_add_lshl_u32 v1, v5, v11, 1
	v_lshl_add_u32 v130, v4, 11, v1
	v_lshl_add_u32 v132, v3, 11, v1
	v_bfe_i32 v1, v10, 27, 1
	v_lshrrev_b32_e32 v1, 22, v1
	v_add_u32_e32 v1, v0, v1
	v_and_b32_e32 v1, 0xfffffc00, v1
	v_sub_u32_e32 v0, v0, v1
	v_lshrrev_b32_e32 v1, 4, v0
	v_ashrrev_i32_e32 v3, 31, v10
	v_bitop3_b32 v0, v1, v0, 32 bitop3:0x6c
	v_lshrrev_b32_e32 v3, 26, v3
	v_ashrrev_i32_e32 v1, 31, v0
	v_add_u32_e32 v3, v10, v3
	v_lshrrev_b32_e32 v1, 26, v1
	v_ashrrev_i32_e32 v13, 6, v3
	v_add_u32_e32 v1, v0, v1
	v_lshlrev_b32_e32 v3, 3, v13
	v_ashrrev_i32_e32 v12, 6, v1
	v_and_b32_e32 v3, -16, v3
	v_add_u32_e32 v3, v12, v3
	v_and_b32_e32 v4, 3, v12
	s_ashr_i32 s14, s69, 31
	v_and_or_b32 v4, v3, s6, v4
	s_lshr_b32 s6, s14, 29
	s_add_i32 s6, s69, s6
	s_ashr_i32 s2, s7, 6
	s_ashr_i32 s11, s6, 3
	s_and_b32 s6, s6, -8
	s_ashr_i32 s10, s7, 8
	s_lshl_b32 s3, s2, 10
	s_sub_i32 s6, s69, s6
	s_cmp_lt_i32 s6, 0
	s_movk_i32 s15, 0xbc
	s_cselect_b32 s18, s15, 0xbb
	s_mul_i32 s6, s6, s18
	s_add_i32 s6, s6, s11
	s_mul_hi_i32 s11, s6, 0x2e8ba2e9
	s_lshr_b32 s18, s11, 31
	s_ashr_i32 s11, s11, 5
	v_lshrrev_b32_e32 v5, 2, v3
	v_lshlrev_b32_e32 v6, 1, v3
	v_and_b32_e32 v1, 0xc0, v1
	s_add_i32 s11, s11, s18
	v_and_b32_e32 v5, 4, v5
	v_and_b32_e32 v6, 24, v6
	v_sub_u32_e32 v0, v0, v1
	s_lshl_b32 s22, s11, 3
	v_or3_b32 v4, v4, v5, v6
	v_lshlrev_b32_e32 v5, 5, v13
	v_ashrrev_i16_sdwa v0, v2, sext(v0) dst_sel:DWORD dst_unused:UNUSED_PAD src0_sel:DWORD src1_sel:BYTE_0
	s_sub_i32 s18, 0x44, s22
	s_mulk_i32 s11, 0xb0
	v_and_b32_e32 v5, 32, v5
	v_bfe_i32 v14, v0, 0, 16
	s_min_u32 s23, s18, 8
	s_sub_i32 s11, s6, s11
	v_add_lshl_u32 v0, v5, v14, 1
	s_sext_i32_i16 s6, s11
	v_cvt_f32_ubyte0_e32 v2, s23
	v_lshl_add_u32 v134, v4, 11, v0
	v_cvt_f32_i32_e32 v1, s6
	v_rcp_iflag_f32_e32 v4, v2
	v_lshl_add_u32 v136, v3, 11, v0
	s_ashr_i32 s6, s6, 30
	s_or_b32 s6, s6, 1
	v_mul_f32_e32 v0, v1, v4
	v_trunc_f32_e32 v0, v0
	v_fma_f32 v1, -v0, v2, v1
	v_cvt_i32_f32_e32 v0, v0
	v_cmp_ge_f32_e64 s[18:19], |v1|, v2
	s_and_b64 s[18:19], s[18:19], exec
	s_cselect_b32 s6, s6, 0
	v_readfirstlane_b32 s18, v0
	s_add_i32 s6, s18, s6
	s_mul_i32 s18, s6, s23
	s_sub_i32 s11, s11, s18
	s_sext_i32_i16 s11, s11
	s_add_i32 s56, s22, s11
	s_ashr_i32 s57, s56, 31
	s_bfe_i64 s[18:19], s[6:7], 0x100000
	s_lshl_b64 s[22:23], s[56:57], 19
	s_lshl_b64 s[18:19], s[18:19], 19
	s_add_u32 s60, s92, s18
	s_addc_u32 s61, s93, s19
	s_add_i32 s18, s3, 0
	s_add_i32 m0, s18, 0x10000
	v_mov_b32_e32 v139, 0
	global_load_lds_dwordx4 v134, s[60:61]
	s_add_i32 m0, s18, 0x12000
	s_add_u32 s24, s60, 0x40000
	global_load_lds_dwordx4 v130, s[60:61]
	s_addc_u32 s25, s61, 0
	s_add_i32 m0, s18, 0x14000
	v_mov_b32_e32 v135, v139
	global_load_lds_dwordx4 v134, s[24:25]
	s_add_i32 m0, s18, 0x16000
	s_add_u32 s58, s94, s22
	s_addc_u32 s59, s95, s23
	s_add_i32 s19, s18, 0x2000
	global_load_lds_dwordx4 v130, s[24:25]
	s_mov_b32 m0, s18
	s_add_u32 s22, s58, 0x40000
	global_load_lds_dwordx4 v136, s[58:59]
	s_mov_b32 m0, s19
	s_addc_u32 s23, s59, 0
	s_add_i32 s35, s18, 0x4000
	global_load_lds_dwordx4 v132, s[58:59]
	s_mov_b32 m0, s35
	s_add_i32 s43, s18, 0x6000
	global_load_lds_dwordx4 v136, s[22:23]
	s_mov_b32 m0, s43
	v_mov_b32_e32 v131, v139
	global_load_lds_dwordx4 v132, s[22:23]
	v_mov_b32_e32 v137, v139
	v_mov_b32_e32 v133, v139
	s_cmp_eq_u32 s10, 1
	s_mov_b32 s11, 0
	v_lshl_add_u64 v[6:7], s[60:61], 0, v[134:135]
	v_lshl_add_u64 v[4:5], s[60:61], 0, v[130:131]
	v_lshl_add_u64 v[0:1], s[58:59], 0, v[136:137]
	s_cselect_b64 s[22:23], -1, 0
	s_cmp_lg_u32 s10, 1
	v_lshl_add_u64 v[2:3], s[58:59], 0, v[132:133]
	s_cbranch_scc1 .LBB0_1652
	s_barrier

.LBB0_1658:
	ds_read_b128 v[152:155], v149
	ds_read_b128 v[156:159], v149 offset:1024
	ds_read_b128 v[160:163], v149 offset:2048
	ds_read_b128 v[166:169], v149 offset:3072
	ds_read_b128 v[170:173], v150
	ds_read_b128 v[174:177], v150 offset:1024
	ds_read_b128 v[178:181], v150 offset:2048
	ds_read_b128 v[182:185], v150 offset:3072
	s_add_u32 s50, s58, 0xfffc0080
	s_addc_u32 s51, s59, -1
	s_cmp_eq_u32 s49, 12
	s_cselect_b32 s63, s33, s51
	s_cselect_b32 s62, s34, s50
	s_cselect_b32 s61, s37, s48
	s_cselect_b32 s60, s39, s42
	buffer_store_dwordx4 v[228:231], v246, s[76:79], s101 offen offset:0 nt
	v_lshl_add_u64 v[218:219], s[58:59], 0, v[140:141]
	s_add_i32 m0, s18, 0xc000
	ds_read_b128 v[186:189], v151
	ds_read_b128 v[190:193], v151 offset:1024
	ds_read_b128 v[194:197], v151 offset:2048
	ds_read_b128 v[198:201], v151 offset:3072
	ds_read_b128 v[202:205], v151 offset:4096
	ds_read_b128 v[206:209], v151 offset:5120
	ds_read_b128 v[210:213], v151 offset:6144
	ds_read_b128 v[214:217], v151 offset:7168
	global_load_lds_dwordx4 v[218:219], off
	v_lshl_add_u64 v[218:219], s[58:59], 0, v[142:143]
	s_add_i32 m0, s18, 0xe000
	s_nop 0
	global_load_lds_dwordx4 v[218:219], off
	buffer_load_dwordx4 v[228:231], v246, s[96:99], s100 offen offset:0 nt
	s_waitcnt vmcnt(11)
	s_waitcnt lgkmcnt(0)
	s_barrier
	s_setprio 1
	s_waitcnt lgkmcnt(0)
	v_mfma_f32_16x16x32_bf16 v[124:127], v[152:155], v[186:189], v[124:127]
	v_mfma_f32_16x16x32_bf16 v[120:123], v[160:163], v[186:189], v[120:123]
	v_mfma_f32_16x16x32_bf16 v[108:111], v[152:155], v[194:197], v[108:111]
	v_mfma_f32_16x16x32_bf16 v[104:107], v[160:163], v[194:197], v[104:107]
	v_mfma_f32_16x16x32_bf16 v[92:95], v[152:155], v[202:205], v[92:95]
	v_mfma_f32_16x16x32_bf16 v[88:91], v[160:163], v[202:205], v[88:91]
	v_mfma_f32_16x16x32_bf16 v[76:79], v[152:155], v[210:213], v[76:79]
	v_mfma_f32_16x16x32_bf16 v[72:75], v[160:163], v[210:213], v[72:75]
	v_mfma_f32_16x16x32_bf16 v[124:127], v[156:159], v[190:193], v[124:127]
	v_mfma_f32_16x16x32_bf16 v[120:123], v[166:169], v[190:193], v[120:123]
	v_mfma_f32_16x16x32_bf16 v[108:111], v[156:159], v[198:201], v[108:111]
	v_mfma_f32_16x16x32_bf16 v[104:107], v[166:169], v[198:201], v[104:107]
	v_mfma_f32_16x16x32_bf16 v[92:95], v[156:159], v[206:209], v[92:95]
	v_mfma_f32_16x16x32_bf16 v[88:91], v[166:169], v[206:209], v[88:91]
	v_mfma_f32_16x16x32_bf16 v[76:79], v[156:159], v[214:217], v[76:79]
	v_mfma_f32_16x16x32_bf16 v[72:75], v[166:169], v[214:217], v[72:75]
	s_setprio 0
	s_setprio 1
	v_mfma_f32_16x16x32_bf16 v[116:119], v[170:173], v[186:189], v[116:119]
	v_mfma_f32_16x16x32_bf16 v[112:115], v[178:181], v[186:189], v[112:115]
	v_mfma_f32_16x16x32_bf16 v[100:103], v[170:173], v[194:197], v[100:103]
	v_mfma_f32_16x16x32_bf16 v[96:99], v[178:181], v[194:197], v[96:99]
	v_mfma_f32_16x16x32_bf16 v[84:87], v[170:173], v[202:205], v[84:87]
	v_mfma_f32_16x16x32_bf16 v[80:83], v[178:181], v[202:205], v[80:83]
	v_mfma_f32_16x16x32_bf16 v[68:71], v[170:173], v[210:213], v[68:71]
	v_mfma_f32_16x16x32_bf16 v[64:67], v[178:181], v[210:213], v[64:67]
	v_mfma_f32_16x16x32_bf16 v[116:119], v[174:177], v[190:193], v[116:119]
	v_mfma_f32_16x16x32_bf16 v[112:115], v[182:185], v[190:193], v[112:115]
	v_mfma_f32_16x16x32_bf16 v[100:103], v[174:177], v[198:201], v[100:103]
	v_mfma_f32_16x16x32_bf16 v[96:99], v[182:185], v[198:201], v[96:99]
	v_mfma_f32_16x16x32_bf16 v[84:87], v[174:177], v[206:209], v[84:87]
	v_mfma_f32_16x16x32_bf16 v[80:83], v[182:185], v[206:209], v[80:83]
	v_mfma_f32_16x16x32_bf16 v[68:71], v[174:177], v[214:217], v[68:71]
	v_mfma_f32_16x16x32_bf16 v[64:67], v[182:185], v[214:217], v[64:67]
	s_setprio 0
	s_barrier
	s_add_i32 s50, s64, s3
	v_lshl_add_u64 v[218:219], s[60:61], 0, v[134:135]
	s_mov_b32 m0, s50
	ds_read_b128 v[186:189], v151 offset:16384
	ds_read_b128 v[190:193], v151 offset:17408
	ds_read_b128 v[194:197], v151 offset:18432
	ds_read_b128 v[198:201], v151 offset:19456
	ds_read_b128 v[202:205], v151 offset:20480
	ds_read_b128 v[206:209], v151 offset:21504
	ds_read_b128 v[210:213], v151 offset:22528
	ds_read_b128 v[214:217], v151 offset:23552
	global_load_lds_dwordx4 v[218:219], off
	s_add_i32 m0, s50, 0x2000
	s_add_u32 s50, s60, 0x40000
	v_lshl_add_u64 v[220:221], s[60:61], 0, v[130:131]
	s_addc_u32 s51, s61, 0
	s_add_i32 s57, s65, s3
	global_load_lds_dwordx4 v[220:221], off
	v_lshl_add_u64 v[222:223], s[50:51], 0, v[134:135]
	s_mov_b32 m0, s57
	v_lshl_add_u64 v[224:225], s[62:63], 0, v[132:133]
	global_load_lds_dwordx4 v[222:223], off
	v_lshl_add_u64 v[222:223], s[50:51], 0, v[130:131]
	s_add_i32 m0, s57, 0x2000
	s_nop 0
	global_load_lds_dwordx4 v[222:223], off
	v_lshl_add_u64 v[222:223], s[62:63], 0, v[136:137]
	s_mov_b32 m0, s18
	s_nop 0
	global_load_lds_dwordx4 v[222:223], off
	s_mov_b32 m0, s19
	s_nop 0
	global_load_lds_dwordx4 v[224:225], off
	s_waitcnt vmcnt(10)
	s_waitcnt lgkmcnt(0)
	s_barrier
	s_setprio 1
	s_waitcnt lgkmcnt(0)
	v_mfma_f32_16x16x32_bf16 v[60:63], v[152:155], v[186:189], v[60:63]
	v_mfma_f32_16x16x32_bf16 v[56:59], v[160:163], v[186:189], v[56:59]
	v_mfma_f32_16x16x32_bf16 v[44:47], v[152:155], v[194:197], v[44:47]
	v_mfma_f32_16x16x32_bf16 v[40:43], v[160:163], v[194:197], v[40:43]
	v_mfma_f32_16x16x32_bf16 v[28:31], v[152:155], v[202:205], v[28:31]
	v_mfma_f32_16x16x32_bf16 v[24:27], v[160:163], v[202:205], v[24:27]
	v_mfma_f32_16x16x32_bf16 v[12:15], v[152:155], v[210:213], v[12:15]
	v_mfma_f32_16x16x32_bf16 v[8:11], v[160:163], v[210:213], v[8:11]
	v_mfma_f32_16x16x32_bf16 v[60:63], v[156:159], v[190:193], v[60:63]
	v_mfma_f32_16x16x32_bf16 v[56:59], v[166:169], v[190:193], v[56:59]
	v_mfma_f32_16x16x32_bf16 v[44:47], v[156:159], v[198:201], v[44:47]
	v_mfma_f32_16x16x32_bf16 v[40:43], v[166:169], v[198:201], v[40:43]
	v_mfma_f32_16x16x32_bf16 v[28:31], v[156:159], v[206:209], v[28:31]
	v_mfma_f32_16x16x32_bf16 v[24:27], v[166:169], v[206:209], v[24:27]
	v_mfma_f32_16x16x32_bf16 v[12:15], v[156:159], v[214:217], v[12:15]
	v_mfma_f32_16x16x32_bf16 v[8:11], v[166:169], v[214:217], v[8:11]
	s_setprio 0
	s_setprio 1
	v_mfma_f32_16x16x32_bf16 v[52:55], v[170:173], v[186:189], v[52:55]
	v_mfma_f32_16x16x32_bf16 v[48:51], v[178:181], v[186:189], v[48:51]
	v_mfma_f32_16x16x32_bf16 v[36:39], v[170:173], v[194:197], v[36:39]
	v_mfma_f32_16x16x32_bf16 v[32:35], v[178:181], v[194:197], v[32:35]
	v_mfma_f32_16x16x32_bf16 v[20:23], v[170:173], v[202:205], v[20:23]
	v_mfma_f32_16x16x32_bf16 v[16:19], v[178:181], v[202:205], v[16:19]
	v_mfma_f32_16x16x32_bf16 v[4:7], v[170:173], v[210:213], v[4:7]
	v_mfma_f32_16x16x32_bf16 v[0:3], v[178:181], v[210:213], v[0:3]
	v_mfma_f32_16x16x32_bf16 v[52:55], v[174:177], v[190:193], v[52:55]
	v_mfma_f32_16x16x32_bf16 v[48:51], v[182:185], v[190:193], v[48:51]
	v_mfma_f32_16x16x32_bf16 v[36:39], v[174:177], v[198:201], v[36:39]
	v_mfma_f32_16x16x32_bf16 v[32:35], v[182:185], v[198:201], v[32:35]
	v_mfma_f32_16x16x32_bf16 v[20:23], v[174:177], v[206:209], v[20:23]
	v_mfma_f32_16x16x32_bf16 v[16:19], v[182:185], v[206:209], v[16:19]
	v_mfma_f32_16x16x32_bf16 v[4:7], v[174:177], v[214:217], v[4:7]
	v_mfma_f32_16x16x32_bf16 v[0:3], v[182:185], v[214:217], v[0:3]
	s_setprio 0
	s_barrier
	buffer_store_dwordx4 v[232:235], v246, s[76:79], s101 offen offset:1024 nt
	s_add_i32 s57, 0, 0x18000
	v_add_u32_e32 v165, s57, v148
	s_add_i32 s68, 0, 0x1c000
	ds_read_b128 v[152:155], v165
	ds_read_b128 v[156:159], v165 offset:1024
	ds_read_b128 v[160:163], v165 offset:2048
	ds_read_b128 v[166:169], v165 offset:3072
	v_add_u32_e32 v165, s68, v148
	ds_read_b128 v[170:173], v165
	ds_read_b128 v[174:177], v165 offset:1024
	ds_read_b128 v[178:181], v165 offset:2048
	ds_read_b128 v[182:185], v165 offset:3072
	s_add_u32 s50, s62, 0x40000
	s_addc_u32 s51, s63, 0
	s_mov_b32 m0, s35
	v_lshl_add_u64 v[226:227], s[50:51], 0, v[136:137]
	ds_read_b128 v[186:189], v151 offset:32768
	ds_read_b128 v[190:193], v151 offset:33792
	ds_read_b128 v[194:197], v151 offset:34816
	ds_read_b128 v[198:201], v151 offset:35840
	ds_read_b128 v[202:205], v151 offset:36864
	ds_read_b128 v[206:209], v151 offset:37888
	ds_read_b128 v[210:213], v151 offset:38912
	ds_read_b128 v[214:217], v151 offset:39936
	global_load_lds_dwordx4 v[226:227], off
	v_lshl_add_u64 v[226:227], s[50:51], 0, v[132:133]
	s_mov_b32 m0, s43
	s_nop 0
	global_load_lds_dwordx4 v[226:227], off
	buffer_load_dwordx4 v[232:235], v246, s[96:99], s100 offen offset:1024 nt
	s_waitcnt vmcnt(11)
	s_waitcnt lgkmcnt(0)
	s_barrier
	s_setprio 1
	s_waitcnt lgkmcnt(0)
	v_mfma_f32_16x16x32_bf16 v[124:127], v[152:155], v[186:189], v[124:127]
	v_mfma_f32_16x16x32_bf16 v[120:123], v[160:163], v[186:189], v[120:123]
	v_mfma_f32_16x16x32_bf16 v[108:111], v[152:155], v[194:197], v[108:111]
	v_mfma_f32_16x16x32_bf16 v[104:107], v[160:163], v[194:197], v[104:107]
	v_mfma_f32_16x16x32_bf16 v[92:95], v[152:155], v[202:205], v[92:95]
	v_mfma_f32_16x16x32_bf16 v[88:91], v[160:163], v[202:205], v[88:91]
	v_mfma_f32_16x16x32_bf16 v[76:79], v[152:155], v[210:213], v[76:79]
	v_mfma_f32_16x16x32_bf16 v[72:75], v[160:163], v[210:213], v[72:75]
	v_mfma_f32_16x16x32_bf16 v[124:127], v[156:159], v[190:193], v[124:127]
	v_mfma_f32_16x16x32_bf16 v[120:123], v[166:169], v[190:193], v[120:123]
	v_mfma_f32_16x16x32_bf16 v[108:111], v[156:159], v[198:201], v[108:111]
	v_mfma_f32_16x16x32_bf16 v[104:107], v[166:169], v[198:201], v[104:107]
	v_mfma_f32_16x16x32_bf16 v[92:95], v[156:159], v[206:209], v[92:95]
	v_mfma_f32_16x16x32_bf16 v[88:91], v[166:169], v[206:209], v[88:91]
	v_mfma_f32_16x16x32_bf16 v[76:79], v[156:159], v[214:217], v[76:79]
	v_mfma_f32_16x16x32_bf16 v[72:75], v[166:169], v[214:217], v[72:75]
	s_setprio 0
	s_setprio 1
	v_mfma_f32_16x16x32_bf16 v[116:119], v[170:173], v[186:189], v[116:119]
	v_mfma_f32_16x16x32_bf16 v[112:115], v[178:181], v[186:189], v[112:115]
	v_mfma_f32_16x16x32_bf16 v[100:103], v[170:173], v[194:197], v[100:103]
	v_mfma_f32_16x16x32_bf16 v[96:99], v[178:181], v[194:197], v[96:99]
	v_mfma_f32_16x16x32_bf16 v[84:87], v[170:173], v[202:205], v[84:87]
	v_mfma_f32_16x16x32_bf16 v[80:83], v[178:181], v[202:205], v[80:83]
	v_mfma_f32_16x16x32_bf16 v[68:71], v[170:173], v[210:213], v[68:71]
	v_mfma_f32_16x16x32_bf16 v[64:67], v[178:181], v[210:213], v[64:67]
	v_mfma_f32_16x16x32_bf16 v[116:119], v[174:177], v[190:193], v[116:119]
	v_mfma_f32_16x16x32_bf16 v[112:115], v[182:185], v[190:193], v[112:115]
	v_mfma_f32_16x16x32_bf16 v[100:103], v[174:177], v[198:201], v[100:103]
	v_mfma_f32_16x16x32_bf16 v[96:99], v[182:185], v[198:201], v[96:99]
	v_mfma_f32_16x16x32_bf16 v[84:87], v[174:177], v[206:209], v[84:87]
	v_mfma_f32_16x16x32_bf16 v[80:83], v[182:185], v[206:209], v[80:83]
	v_mfma_f32_16x16x32_bf16 v[68:71], v[174:177], v[214:217], v[68:71]
	v_mfma_f32_16x16x32_bf16 v[64:67], v[182:185], v[214:217], v[64:67]
	s_setprio 0
	s_barrier
	s_add_i32 s50, s57, s3
	v_lshl_add_u64 v[218:219], v[218:219], 0, s[24:25]
	s_mov_b32 m0, s50
	ds_read_b128 v[186:189], v151 offset:49152
	ds_read_b128 v[190:193], v151 offset:50176
	ds_read_b128 v[194:197], v151 offset:51200
	ds_read_b128 v[198:201], v151 offset:52224
	ds_read_b128 v[202:205], v151 offset:53248
	ds_read_b128 v[206:209], v151 offset:54272
	ds_read_b128 v[210:213], v151 offset:55296
	ds_read_b128 v[214:217], v151 offset:56320
	global_load_lds_dwordx4 v[218:219], off
	s_add_i32 m0, s50, 0x2000
	s_add_u32 s50, s60, 0x40080
	v_lshl_add_u64 v[218:219], v[220:221], 0, s[24:25]
	s_addc_u32 s51, s61, 0
	s_add_i32 s57, s68, s3
	global_load_lds_dwordx4 v[218:219], off
	v_lshl_add_u64 v[218:219], s[50:51], 0, v[134:135]
	s_mov_b32 m0, s57
	s_nop 0
	global_load_lds_dwordx4 v[218:219], off
	v_lshl_add_u64 v[218:219], s[50:51], 0, v[130:131]
	s_add_i32 m0, s57, 0x2000
	s_nop 0
	global_load_lds_dwordx4 v[218:219], off
	v_lshl_add_u64 v[218:219], v[222:223], 0, s[24:25]
	s_mov_b32 m0, s44
	s_nop 0
	global_load_lds_dwordx4 v[218:219], off
	v_lshl_add_u64 v[218:219], v[224:225], 0, s[24:25]
	s_mov_b32 m0, s45
	s_nop 0
	global_load_lds_dwordx4 v[218:219], off
	s_waitcnt vmcnt(10)
	s_waitcnt lgkmcnt(0)
	s_barrier
	s_setprio 1
	s_waitcnt lgkmcnt(0)
	v_mfma_f32_16x16x32_bf16 v[60:63], v[152:155], v[186:189], v[60:63]
	v_mfma_f32_16x16x32_bf16 v[56:59], v[160:163], v[186:189], v[56:59]
	v_mfma_f32_16x16x32_bf16 v[44:47], v[152:155], v[194:197], v[44:47]
	v_mfma_f32_16x16x32_bf16 v[40:43], v[160:163], v[194:197], v[40:43]
	v_mfma_f32_16x16x32_bf16 v[28:31], v[152:155], v[202:205], v[28:31]
	v_mfma_f32_16x16x32_bf16 v[24:27], v[160:163], v[202:205], v[24:27]
	v_mfma_f32_16x16x32_bf16 v[12:15], v[152:155], v[210:213], v[12:15]
	v_mfma_f32_16x16x32_bf16 v[8:11], v[160:163], v[210:213], v[8:11]
	v_mfma_f32_16x16x32_bf16 v[60:63], v[156:159], v[190:193], v[60:63]
	v_mfma_f32_16x16x32_bf16 v[56:59], v[166:169], v[190:193], v[56:59]
	v_mfma_f32_16x16x32_bf16 v[44:47], v[156:159], v[198:201], v[44:47]
	v_mfma_f32_16x16x32_bf16 v[40:43], v[166:169], v[198:201], v[40:43]
	v_mfma_f32_16x16x32_bf16 v[28:31], v[156:159], v[206:209], v[28:31]
	v_mfma_f32_16x16x32_bf16 v[24:27], v[166:169], v[206:209], v[24:27]
	v_mfma_f32_16x16x32_bf16 v[12:15], v[156:159], v[214:217], v[12:15]
	v_mfma_f32_16x16x32_bf16 v[8:11], v[166:169], v[214:217], v[8:11]
	s_setprio 0
	s_setprio 1
	v_mfma_f32_16x16x32_bf16 v[52:55], v[170:173], v[186:189], v[52:55]
	v_mfma_f32_16x16x32_bf16 v[48:51], v[178:181], v[186:189], v[48:51]
	v_mfma_f32_16x16x32_bf16 v[36:39], v[170:173], v[194:197], v[36:39]
	v_mfma_f32_16x16x32_bf16 v[32:35], v[178:181], v[194:197], v[32:35]
	v_mfma_f32_16x16x32_bf16 v[20:23], v[170:173], v[202:205], v[20:23]
	v_mfma_f32_16x16x32_bf16 v[16:19], v[178:181], v[202:205], v[16:19]
	v_mfma_f32_16x16x32_bf16 v[4:7], v[170:173], v[210:213], v[4:7]
	v_mfma_f32_16x16x32_bf16 v[0:3], v[178:181], v[210:213], v[0:3]
	v_mfma_f32_16x16x32_bf16 v[52:55], v[174:177], v[190:193], v[52:55]
	v_mfma_f32_16x16x32_bf16 v[48:51], v[182:185], v[190:193], v[48:51]
	v_mfma_f32_16x16x32_bf16 v[36:39], v[174:177], v[198:201], v[36:39]
	v_mfma_f32_16x16x32_bf16 v[32:35], v[182:185], v[198:201], v[32:35]
	v_mfma_f32_16x16x32_bf16 v[20:23], v[174:177], v[206:209], v[20:23]
	v_mfma_f32_16x16x32_bf16 v[16:19], v[182:185], v[206:209], v[16:19]
	v_mfma_f32_16x16x32_bf16 v[4:7], v[174:177], v[214:217], v[4:7]
	v_mfma_f32_16x16x32_bf16 v[0:3], v[182:185], v[214:217], v[0:3]
	s_setprio 0
	s_barrier
	s_mov_b32 s101, s100
	s_add_i32 s32, s32, 1
	s_cmp_eq_u32 s32, 6
	s_cselect_b32 vcc_lo, 0x3000, 0
	s_cselect_b32 s32, 0, s32
	s_add_u32 s100, s100, vcc_lo
	s_addk_i32 s100, 0x800
	s_sub_u32 s4, s4, 1
	s_cmp_eq_u32 s4, 0
	s_cselect_b32 s98, 0, s98
	s_cselect_b32 s78, 0, s78
	s_add_i32 s49, s49, 2
	s_add_u32 s58, s58, 0x100
	s_addc_u32 s59, s59, 0
	s_add_u32 s42, s42, 0x100
	s_addc_u32 s48, s48, 0
	s_cmp_gt_u32 s49, 13
	s_cbranch_scc0 .LBB0_1658
	s_and_b64 vcc, exec, s[26:27]
	s_cbranch_vccz .LBB0_1661
	s_barrier

.LBB0_1664:
	v_readlane_b32 s78, v247, 0
	v_readlane_b32 s79, v247, 1
	v_readlane_b32 s4, v247, 2
	s_waitcnt vmcnt(0)
	s_barrier

	.amdhsa_kernel _Z10fwd_kernel6Params
		.amdhsa_group_segment_fixed_size 0
		.amdhsa_private_segment_fixed_size 0
		.amdhsa_kernarg_size 432
		.amdhsa_user_sgpr_count 2
		.amdhsa_user_sgpr_dispatch_ptr 0
		.amdhsa_user_sgpr_queue_ptr 0
		.amdhsa_user_sgpr_kernarg_segment_ptr 1
		.amdhsa_user_sgpr_dispatch_id 0
		.amdhsa_user_sgpr_kernarg_preload_length 0
		.amdhsa_user_sgpr_kernarg_preload_offset 0
		.amdhsa_user_sgpr_private_segment_size 0
		.amdhsa_uses_dynamic_stack 0
		.amdhsa_enable_private_segment 0
		.amdhsa_system_sgpr_workgroup_id_x 1
		.amdhsa_system_sgpr_workgroup_id_y 0
		.amdhsa_system_sgpr_workgroup_id_z 0
		.amdhsa_system_sgpr_workgroup_info 0
		.amdhsa_system_vgpr_workitem_id 2
		.amdhsa_next_free_vgpr 248
		.amdhsa_next_free_sgpr 102
		.amdhsa_accum_offset 248
		.amdhsa_reserve_vcc 1
		.amdhsa_float_round_mode_32 0
		.amdhsa_float_round_mode_16_64 0
		.amdhsa_float_denorm_mode_32 3
		.amdhsa_float_denorm_mode_16_64 3
		.amdhsa_dx10_clamp 1
		.amdhsa_ieee_mode 1
		.amdhsa_fp16_overflow 0
		.amdhsa_tg_split 0
		.amdhsa_exception_fp_ieee_invalid_op 0
		.amdhsa_exception_fp_denorm_src 0
		.amdhsa_exception_fp_ieee_div_zero 0
		.amdhsa_exception_fp_ieee_overflow 0
		.amdhsa_exception_fp_ieee_underflow 0
		.amdhsa_exception_fp_ieee_inexact 0
		.amdhsa_exception_int_div_zero 0
	.end_amdhsa_kernel

amdhsa.kernels:
  - .agpr_count:     0
    .args:
      - .offset:         0
        .size:           176
        .value_kind:     by_value
      - .offset:         176
        .size:           4
        .value_kind:     hidden_block_count_x
      - .offset:         180
        .size:           4
        .value_kind:     hidden_block_count_y
      - .offset:         184
        .size:           4
        .value_kind:     hidden_block_count_z
      - .offset:         188
        .size:           2
        .value_kind:     hidden_group_size_x
      - .offset:         190
        .size:           2
        .value_kind:     hidden_group_size_y
      - .offset:         192
        .size:           2
        .value_kind:     hidden_group_size_z
      - .offset:         194
        .size:           2
        .value_kind:     hidden_remainder_x
      - .offset:         196
        .size:           2
        .value_kind:     hidden_remainder_y
      - .offset:         198
        .size:           2
        .value_kind:     hidden_remainder_z
      - .offset:         216
        .size:           8
        .value_kind:     hidden_global_offset_x
      - .offset:         224
        .size:           8
        .value_kind:     hidden_global_offset_y
      - .offset:         232
        .size:           8
        .value_kind:     hidden_global_offset_z
      - .offset:         240
        .size:           2
        .value_kind:     hidden_grid_dims
      - .offset:         264
        .size:           8
        .value_kind:     hidden_multigrid_sync_arg
      - .offset:         296
        .size:           4
        .value_kind:     hidden_dynamic_lds_size
    .group_segment_fixed_size: 0
    .kernarg_segment_align: 8
    .kernarg_segment_size: 432
    .language:       OpenCL C
    .language_version:
      - 2
      - 0
    .max_flat_workgroup_size: 512
    .name:           _Z10fwd_kernel6Params
    .private_segment_fixed_size: 0
    .sgpr_count:     108
    .sgpr_spill_count: 24
    .symbol:         _Z10fwd_kernel6Params.kd
    .uniform_work_group_size: 1
    .uses_dynamic_stack: false
    .vgpr_count:     248
    .vgpr_spill_count: 0
    .wavefront_size: 64
